# P2b producer prologue: 3 history-row loads issued without waits into spare regs, unpacked after the 8 main loads are in flight (removes 2 serialized round trips per item)
# speedup vs baseline: 1.0017x; 1.0017x over previous
.LBB0_182:
	s_andn2_saveexec_b64 s[74:75], s[74:75]
	s_cbranch_execz .LBB0_160
	global_load_dwordx4 v[0:3], v[138:139], off offset:16
	global_load_dwordx4 v[4:7], v[138:139], off
	global_load_dwordx4 v[8:11], v[140:141], off offset:16
	global_load_dwordx4 v[12:15], v[140:141], off
	global_load_dwordx4 v[16:19], v[142:143], off offset:16
	global_load_dwordx4 v[20:23], v[142:143], off
	global_load_dwordx4 v[24:27], v[144:145], off offset:16
	global_load_dwordx4 v[28:31], v[144:145], off
	global_load_dwordx4 v[32:35], v[146:147], off offset:16
	global_load_dwordx4 v[36:39], v[146:147], off
	s_cmp_eq_u32 s29, 0
	s_cselect_b64 s[30:31], -1, 0
	s_or_b64 s[30:31], s[24:25], s[30:31]
	s_mov_b64 s[76:77], -1
	s_and_b64 vcc, exec, s[30:31]
	s_cbranch_vccnz .LBB0_185
	s_add_i32 s29, s28, -3
	v_mad_i64_i32 v[40:41], s[30:31], s29, v207, v[134:135]
	s_add_i32 s29, s28, -2
	s_add_i32 s28, s28, -1
	v_mad_i64_i32 v[44:45], s[30:31], s29, v207, v[134:135]
	v_mad_i64_i32 v[48:49], s[28:29], s28, v207, v[134:135]
	global_load_dwordx4 v[208:211], v[40:41], off
	s_mov_b64 s[76:77], 0
	global_load_dwordx4 v[212:215], v[44:45], off
	global_load_dwordx4 v[216:219], v[48:49], off

.LBB0_188:
	s_mul_i32 s28, s3, 0x1200
	v_add_u32_e32 v136, s28, v132
	v_lshl_add_u64 v[40:41], v[136:137], 1, s[26:27]
	v_add_u32_e32 v42, 0x1200, v136
	v_mov_b32_e32 v43, v137
	v_lshl_add_u64 v[42:43], v[42:43], 1, s[26:27]
	global_load_dwordx4 v[68:71], v[40:41], off
	global_load_dwordx4 v[64:67], v[42:43], off
	v_add_u32_e32 v40, 0x2400, v136
	v_mov_b32_e32 v41, v137
	v_lshl_add_u64 v[40:41], v[40:41], 1, s[26:27]
	v_add_u32_e32 v42, 0x3600, v136
	v_mov_b32_e32 v43, v137
	v_lshl_add_u64 v[42:43], v[42:43], 1, s[26:27]
	global_load_dwordx4 v[60:63], v[40:41], off
	global_load_dwordx4 v[56:59], v[42:43], off
	v_add_u32_e32 v40, 0x4800, v136
	v_mov_b32_e32 v41, v137
	v_lshl_add_u64 v[40:41], v[40:41], 1, s[26:27]
	v_add_u32_e32 v42, 0x5a00, v136
	v_mov_b32_e32 v43, v137
	v_lshl_add_u64 v[42:43], v[42:43], 1, s[26:27]
	global_load_dwordx4 v[52:55], v[40:41], off
	global_load_dwordx4 v[48:51], v[42:43], off
	v_add_u32_e32 v40, 0x6c00, v136
	v_mov_b32_e32 v41, v137
	v_add_u32_e32 v136, 0x7e00, v136
	v_lshl_add_u64 v[40:41], v[40:41], 1, s[26:27]
	v_lshl_add_u64 v[42:43], v[136:137], 1, s[26:27]
	global_load_dwordx4 v[44:47], v[40:41], off
	s_nop 0
	global_load_dwordx4 v[40:43], v[42:43], off
	s_and_b64 vcc, exec, s[76:77]
	s_cbranch_vccnz .Lp2b_hist_done
	s_waitcnt vmcnt(8)
	v_lshlrev_b32_e32 v108, 16, v208
	v_and_b32_e32 v109, 0xffff0000, v208
	v_lshlrev_b32_e32 v110, 16, v209
	v_and_b32_e32 v111, 0xffff0000, v209
	v_lshlrev_b32_e32 v104, 16, v210
	v_and_b32_e32 v105, 0xffff0000, v210
	v_lshlrev_b32_e32 v106, 16, v211
	v_and_b32_e32 v107, 0xffff0000, v211
	v_lshlrev_b32_e32 v120, 16, v212
	v_and_b32_e32 v121, 0xffff0000, v212
	v_lshlrev_b32_e32 v122, 16, v213
	v_and_b32_e32 v123, 0xffff0000, v213
	v_lshlrev_b32_e32 v124, 16, v214
	v_and_b32_e32 v125, 0xffff0000, v214
	v_lshlrev_b32_e32 v126, 16, v215
	v_and_b32_e32 v127, 0xffff0000, v215
	v_lshlrev_b32_e32 v116, 16, v216
	v_and_b32_e32 v117, 0xffff0000, v216
	v_lshlrev_b32_e32 v118, 16, v217
	v_and_b32_e32 v119, 0xffff0000, v217
	v_lshlrev_b32_e32 v112, 16, v218
	v_and_b32_e32 v113, 0xffff0000, v218
	v_lshlrev_b32_e32 v114, 16, v219
	v_and_b32_e32 v115, 0xffff0000, v219
.Lp2b_hist_done:
	v_add_u32_e32 v168, s28, v201
	v_lshl_add_u32 v170, s3, 10, v130
	v_lshl_add_u32 v163, s3, 9, v202
	s_mov_b32 s88, 0
	s_mov_b32 s89, 0
	s_branch .LBB0_190
